# v21 plus: MLA attention loop issues the next K tile loads at the start of the second half-iteration instead of at the loop latch
# speedup vs baseline: 1.0069x; 1.0038x over previous
.LBB0_184:
	v_mov_b32_e32 v228, v13
	v_mov_b32_e32 v0, v12
	v_mov_b32_e32 v227, v224
	v_mov_b32_e32 v11, v15
	s_mov_b64 s[0:1], exec
	s_branch .LBB0_186

.LBB0_190:
	s_xor_b32 vcc_lo, s0, 1
	s_mul_i32 vcc_lo, vcc_lo, 0x3400
	v_add_u32_e32 v219, vcc_lo, v202
	v_add_u32_e32 v253, vcc_lo, v223
	s_waitcnt vmcnt(1)
	ds_write_b128 v219, v[6:9]
	s_and_saveexec_b64 s[100:101], s[6:7]
	ds_write_b128 v253, v[144:147] offset:128
	s_or_b64 exec, exec, s[100:101]
	s_waitcnt lgkmcnt(0)
	s_barrier
	v_lshl_add_u64 v[206:207], v[206:207], 0, s[56:57]
	v_lshl_add_u64 v[208:209], v[208:209], 0, s[58:59]
	global_load_dwordx4 v[6:9], v[206:207], off
	s_and_saveexec_b64 s[100:101], s[6:7]
	s_cbranch_execz .Lmla_nok2
	global_load_dwordx4 v[144:147], v[208:209], off
.Lmla_nok2:
	s_or_b64 exec, exec, s[100:101]
	s_mul_i32 s1, s0, 0x2400
	v_sub_f32_e32 v14, v128, v12
	v_sub_f32_e32 v128, v130, v12
	v_sub_f32_e32 v130, v132, v12
	v_sub_f32_e32 v132, v134, v12
	v_sub_f32_e32 v134, v136, v12
	v_sub_f32_e32 v136, v138, v12
	v_sub_f32_e32 v138, v140, v12
	v_sub_f32_e32 v140, v142, v12
	v_add_u32_e32 v142, s1, v222
	ds_read_b128 v[244:247], v142 offset:26624
	ds_read_b128 v[248:251], v142 offset:26656
	v_sub_f32_e32 v15, v112, v12
	v_sub_f32_e32 v112, v129, v12
	v_sub_f32_e32 v129, v131, v12
	v_sub_f32_e32 v131, v133, v12
	v_sub_f32_e32 v133, v135, v12
	v_sub_f32_e32 v135, v137, v12
	v_sub_f32_e32 v137, v139, v12
	v_sub_f32_e32 v139, v141, v12
	v_sub_f32_e32 v141, v143, v12
	v_sub_f32_e32 v96, v96, v13
	v_sub_f32_e32 v97, v97, v13
	v_sub_f32_e32 v98, v98, v13
	v_sub_f32_e32 v99, v99, v13
	v_sub_f32_e32 v100, v100, v13
	v_sub_f32_e32 v101, v101, v13
	v_sub_f32_e32 v102, v102, v13
	v_sub_f32_e32 v143, v86, v13
	v_sub_f32_e32 v86, v103, v13
	v_exp_f32_e32 v14, v14
	v_exp_f32_e32 v112, v112
	v_exp_f32_e32 v128, v128
	v_exp_f32_e32 v129, v129
	v_exp_f32_e32 v130, v130
	v_exp_f32_e32 v131, v131
	v_exp_f32_e32 v132, v132
	v_exp_f32_e32 v133, v133
	v_exp_f32_e32 v96, v96
	v_exp_f32_e32 v97, v97
	v_exp_f32_e32 v98, v98
	v_exp_f32_e32 v99, v99
	v_exp_f32_e32 v100, v100
	v_exp_f32_e32 v101, v101
	v_exp_f32_e32 v102, v102
	v_exp_f32_e32 v86, v86
	v_cvt_pk_bf16_f32 v228, v14, v112
	v_cvt_pk_bf16_f32 v229, v128, v129
	v_cvt_pk_bf16_f32 v230, v130, v131
	v_cvt_pk_bf16_f32 v231, v132, v133
	v_cvt_pk_bf16_f32 v210, v96, v97
	v_cvt_pk_bf16_f32 v211, v98, v99
	v_cvt_pk_bf16_f32 v212, v100, v101
	v_cvt_pk_bf16_f32 v213, v102, v86
	s_waitcnt lgkmcnt(1)
	v_mfma_f32_32x32x16_bf16 v[64:79], v[244:247], v[228:231], v[64:79]
	v_sub_f32_e32 v103, v104, v13
	v_sub_f32_e32 v104, v105, v13
	v_sub_f32_e32 v105, v106, v13
	v_sub_f32_e32 v106, v107, v13
	v_sub_f32_e32 v107, v108, v13
	v_sub_f32_e32 v108, v109, v13
	v_sub_f32_e32 v109, v110, v13
	v_mfma_f32_32x32x16_bf16 v[32:47], v[244:247], v[210:213], v[32:47]
	v_sub_f32_e32 v110, v111, v13
	v_exp_f32_e32 v134, v134
	v_exp_f32_e32 v135, v135
	v_exp_f32_e32 v136, v136
	v_exp_f32_e32 v137, v137
	v_exp_f32_e32 v138, v138
	v_exp_f32_e32 v139, v139
	v_exp_f32_e32 v140, v140
	v_exp_f32_e32 v141, v141
	v_exp_f32_e32 v103, v103
	v_exp_f32_e32 v104, v104
	v_exp_f32_e32 v105, v105
	v_exp_f32_e32 v106, v106
	v_exp_f32_e32 v107, v107
	v_exp_f32_e32 v108, v108
	v_exp_f32_e32 v109, v109
	v_exp_f32_e32 v110, v110
	v_cvt_pk_bf16_f32 v232, v134, v135
	v_cvt_pk_bf16_f32 v233, v136, v137
	v_cvt_pk_bf16_f32 v234, v138, v139
	v_cvt_pk_bf16_f32 v235, v140, v141
	v_cvt_pk_bf16_f32 v244, v103, v104
	v_cvt_pk_bf16_f32 v245, v105, v106
	v_cvt_pk_bf16_f32 v246, v107, v108
	v_cvt_pk_bf16_f32 v247, v109, v110
	ds_read_b128 v[198:201], v142 offset:26688
	s_waitcnt lgkmcnt(1)
	v_mfma_f32_32x32x16_bf16 v[64:79], v[248:251], v[232:235], v[64:79]
	v_sub_f32_e32 v113, v113, v12
	v_sub_f32_e32 v114, v114, v12
	v_sub_f32_e32 v115, v115, v12
	v_sub_f32_e32 v116, v116, v12
	v_sub_f32_e32 v117, v117, v12
	v_sub_f32_e32 v118, v118, v12
	v_sub_f32_e32 v119, v119, v12
	v_mfma_f32_32x32x16_bf16 v[32:47], v[248:251], v[244:247], v[32:47]
	v_sub_f32_e32 v80, v80, v13
	v_sub_f32_e32 v81, v81, v13
	v_sub_f32_e32 v82, v82, v13
	v_sub_f32_e32 v83, v83, v13
	v_sub_f32_e32 v84, v84, v13
	v_sub_f32_e32 v85, v85, v13
	v_sub_f32_e32 v87, v87, v13
	v_exp_f32_e32 v15, v15
	v_exp_f32_e32 v113, v113
	v_exp_f32_e32 v114, v114
	v_exp_f32_e32 v115, v115
	v_exp_f32_e32 v116, v116
	v_exp_f32_e32 v117, v117
	v_exp_f32_e32 v118, v118
	v_exp_f32_e32 v119, v119
	v_exp_f32_e32 v80, v80
	v_exp_f32_e32 v81, v81
	v_exp_f32_e32 v82, v82
	v_exp_f32_e32 v83, v83
	v_exp_f32_e32 v84, v84
	v_exp_f32_e32 v85, v85
	v_exp_f32_e32 v111, v143
	v_exp_f32_e32 v87, v87
	v_cvt_pk_bf16_f32 v236, v15, v113
	v_cvt_pk_bf16_f32 v237, v114, v115
	v_cvt_pk_bf16_f32 v238, v116, v117
	v_cvt_pk_bf16_f32 v239, v118, v119
	ds_read_b128 v[248:251], v142 offset:26720
	v_cvt_pk_bf16_f32 v214, v80, v81
	v_cvt_pk_bf16_f32 v215, v82, v83
	v_cvt_pk_bf16_f32 v216, v84, v85
	v_cvt_pk_bf16_f32 v217, v111, v87
	s_waitcnt lgkmcnt(1)
	v_mfma_f32_32x32x16_bf16 v[64:79], v[198:201], v[236:239], v[64:79]
	v_sub_f32_e32 v120, v120, v12
	v_sub_f32_e32 v121, v121, v12
	v_sub_f32_e32 v122, v122, v12
	v_sub_f32_e32 v123, v123, v12
	v_sub_f32_e32 v124, v124, v12
	v_sub_f32_e32 v125, v125, v12
	v_sub_f32_e32 v126, v126, v12
	v_mfma_f32_32x32x16_bf16 v[32:47], v[198:201], v[214:217], v[32:47]
	v_sub_f32_e32 v127, v127, v12
	v_sub_f32_e32 v88, v88, v13
	v_sub_f32_e32 v89, v89, v13
	v_sub_f32_e32 v90, v90, v13
	v_sub_f32_e32 v91, v91, v13
	v_sub_f32_e32 v92, v92, v13
	v_sub_f32_e32 v93, v93, v13
	v_sub_f32_e32 v94, v94, v13
	v_sub_f32_e32 v95, v95, v13
	v_exp_f32_e32 v120, v120
	v_exp_f32_e32 v121, v121
	v_exp_f32_e32 v122, v122
	v_exp_f32_e32 v123, v123
	v_exp_f32_e32 v124, v124
	v_exp_f32_e32 v125, v125
	v_exp_f32_e32 v126, v126
	v_exp_f32_e32 v127, v127
	v_exp_f32_e32 v88, v88
	v_exp_f32_e32 v89, v89
	v_exp_f32_e32 v90, v90
	v_exp_f32_e32 v91, v91
	v_exp_f32_e32 v92, v92
	v_exp_f32_e32 v93, v93
	v_exp_f32_e32 v94, v94
	v_exp_f32_e32 v95, v95
	v_cvt_pk_bf16_f32 v240, v120, v121
	v_cvt_pk_bf16_f32 v241, v122, v123
	v_cvt_pk_bf16_f32 v242, v124, v125
	v_cvt_pk_bf16_f32 v243, v126, v127
	v_cvt_pk_bf16_f32 v198, v88, v89
	v_cvt_pk_bf16_f32 v199, v90, v91
	v_cvt_pk_bf16_f32 v200, v92, v93
	v_cvt_pk_bf16_f32 v201, v94, v95
	s_waitcnt lgkmcnt(0)
	v_mfma_f32_32x32x16_bf16 v[64:79], v[248:251], v[240:243], v[64:79]
	s_xor_b32 s5, s0, 1
	s_mul_i32 s0, s5, 0x3400
	s_add_i32 s34, s0, 0
	v_mfma_f32_32x32x16_bf16 v[32:47], v[248:251], v[198:201], v[32:47]
	ds_read_b128 v[248:251], v142 offset:31232
	s_waitcnt lgkmcnt(0)
	v_mfma_f32_32x32x16_bf16 v[16:31], v[248:251], v[210:213], v[16:31]
	ds_read_b128 v[210:213], v142 offset:31264
	v_mfma_f32_32x32x16_bf16 v[48:63], v[248:251], v[228:231], v[48:63]
	s_waitcnt lgkmcnt(0)
	v_mfma_f32_32x32x16_bf16 v[48:63], v[210:213], v[232:235], v[48:63]
	v_mfma_f32_32x32x16_bf16 v[16:31], v[210:213], v[244:247], v[16:31]
	ds_read_b128 v[210:213], v142 offset:31296
	s_waitcnt lgkmcnt(0)
	v_mfma_f32_32x32x16_bf16 v[48:63], v[210:213], v[236:239], v[48:63]
	v_mfma_f32_32x32x16_bf16 v[16:31], v[210:213], v[214:217], v[16:31]
	ds_read_b128 v[210:213], v142 offset:31328
	s_waitcnt lgkmcnt(0)
	v_mfma_f32_32x32x16_bf16 v[48:63], v[210:213], v[240:243], v[48:63]
	v_mfma_f32_32x32x16_bf16 v[16:31], v[210:213], v[198:201], v[16:31]
	v_add_f32_e32 v219, v96, v80
	v_add_f32_e32 v219, 0, v219
	v_add_f32_e32 v253, v97, v81
	v_add_f32_e32 v219, v253, v219
	v_add_f32_e32 v253, v98, v82
	v_add_f32_e32 v219, v253, v219
	v_add_f32_e32 v253, v99, v83
	v_add_f32_e32 v219, v253, v219
	v_add_f32_e32 v253, v100, v84
	v_add_f32_e32 v219, v253, v219
	v_add_f32_e32 v253, v101, v85
	v_add_f32_e32 v219, v253, v219
	v_add_f32_e32 v253, v102, v111
	v_add_f32_e32 v219, v253, v219
	v_add_f32_e32 v253, v86, v87
	v_add_f32_e32 v219, v253, v219
	v_add_f32_e32 v253, v103, v88
	v_add_f32_e32 v219, v253, v219
	v_add_f32_e32 v253, v104, v89
	v_add_f32_e32 v219, v253, v219
	v_add_f32_e32 v253, v105, v90
	v_add_f32_e32 v219, v253, v219
	v_add_f32_e32 v253, v106, v91
	v_add_f32_e32 v219, v253, v219
	v_add_f32_e32 v253, v107, v92
	v_add_f32_e32 v219, v253, v219
	v_add_f32_e32 v253, v108, v93
	v_add_f32_e32 v219, v253, v219
	v_add_f32_e32 v253, v109, v94
	v_add_f32_e32 v219, v253, v219
	v_add_f32_e32 v253, v110, v95
	v_add_f32_e32 v224, v253, v219
	v_add_f32_e32 v219, v14, v15
	v_add_f32_e32 v219, 0, v219
	v_add_f32_e32 v253, v112, v113
	v_add_f32_e32 v219, v253, v219
	v_add_f32_e32 v253, v128, v114
	v_add_f32_e32 v219, v253, v219
	v_add_f32_e32 v253, v129, v115
	v_add_f32_e32 v219, v253, v219
	v_add_f32_e32 v253, v130, v116
	v_add_f32_e32 v219, v253, v219
	v_add_f32_e32 v253, v131, v117
	v_add_f32_e32 v219, v253, v219
	v_add_f32_e32 v253, v132, v118
	v_add_f32_e32 v219, v253, v219
	v_add_f32_e32 v253, v133, v119
	v_add_f32_e32 v219, v253, v219
	v_add_f32_e32 v253, v134, v120
	v_add_f32_e32 v219, v253, v219
	v_add_f32_e32 v253, v135, v121
	v_add_f32_e32 v219, v253, v219
	v_add_f32_e32 v253, v136, v122
	v_add_f32_e32 v219, v253, v219
	v_add_f32_e32 v253, v137, v123
	v_add_f32_e32 v219, v253, v219
	v_add_f32_e32 v253, v138, v124
	v_add_f32_e32 v219, v253, v219
	v_add_f32_e32 v253, v139, v125
	v_add_f32_e32 v219, v253, v219
	v_add_f32_e32 v253, v140, v126
	v_add_f32_e32 v219, v253, v219
	v_add_f32_e32 v253, v141, v127
	s_mulk_i32 s5, 0x2400
	v_add_f32_e32 v15, v253, v219
	v_fmac_f32_e32 v15, v11, v0
	s_add_i32 s4, s4, 1
	v_add_u32_e32 v0, s5, v226
	v_fmac_f32_e32 v224, v227, v10
	v_add_u32_e32 v0, 0x6800, v0
	v_lshl_add_u64 v[204:205], v[204:205], 0, s[84:85]
	s_cmpk_eq_i32 s4, 0x47
	s_waitcnt vmcnt(1)
	ds_write2_b64 v0, v[2:3], v[4:5] offset1:2
	s_waitcnt lgkmcnt(0)
	s_barrier
	s_cbranch_scc0 .LBB0_184
	s_waitcnt vmcnt(0)
	s_cmp_eq_u64 s[6:7], 0
	s_cbranch_scc1 .Lmla_stag_out
	s_barrier
